# K-split partial-sum slab stores written through (sc1) so the release fence before the reduce pass has less to write back
# speedup vs baseline: 1.0046x; 1.0042x over previous
; __device__ __forceinline__ unsigned cvt_pk_bf16(float lo, float hi) { unsigned r; asm volatile("v_cvt_pk_bf16_f32 %0, %1, %2" : "=v"(r) : "v"(lo), "v"(hi)); return r; }
; template <class Desc, class Epi, bool ALIGN_EPI>
; __device__ __forceinline__ void gemm_phase(LAS unsigned char* lds, const Desc& D, const Epi& E, int G, int c) {
;     ...
;           if constexpr (Desc::SPLIT) {
;               if (cur.sp >= 0) {
;                   const __amdgpu_buffer_rsrc_t rs = __builtin_amdgcn_make_buffer_rsrc((void*)(D.slab + (size_t)(cur.uid * Desc::S + cur.sp) * SLAB_B), (short)0, SLAB_B, 0x00020000);
;                   const int loff = ((wr_ * 4 + wc_) * 16 * 64 + ln_) * 16;
; #pragma unroll
;                   for (int rp = 0; rp < 16; ++rp) { const f32x4 a0 = acc[rp >> 3][(rp >> 2) & 1][rp & 3][0], a1 = acc[rp >> 3][(rp >> 2) & 1][rp & 3][1];
;                       u32x4 w; w.x = cvt_pk_bf16(a0[0], a0[1]); w.y = cvt_pk_bf16(a0[2], a0[3]); w.z = cvt_pk_bf16(a1[0], a1[1]); w.w = cvt_pk_bf16(a1[2], a1[3]);
;                       __builtin_amdgcn_raw_buffer_store_b128(w, rs, loff, rp * 1024, 0); }
;                   slabbed = true;
;               }
.LBB0_193:
	s_and_b64 vcc, exec, s[12:13]
	s_cbranch_vccz .LBB0_456
	s_lshl_b32 s2, s23, 1
	s_add_i32 s2, s2, s96
	s_ashr_i32 s3, s2, 31
	s_lshl_b64 s[2:3], s[2:3], 17
	v_readlane_b32 s12, v255, 19
	s_add_u32 s20, s12, s2
	v_readlane_b32 s2, v255, 20
	s_addc_u32 s2, s2, s3
	s_and_b32 s21, s2, 0xffff
	s_lshl_b32 s2, s57, 16
	s_lshl_b32 s3, s9, 14
	s_add_i32 s2, s2, s3
	s_mov_b32 s23, s22
	v_lshl_add_u32 v132, v173, 4, s2
	s_movk_i32 s2, 0x400
	v_cvt_pk_bf16_f32 v128, v128, v129
	v_cvt_pk_bf16_f32 v129, v130, v131
	v_cvt_pk_bf16_f32 v130, v124, v125
	v_cvt_pk_bf16_f32 v131, v126, v127
	buffer_store_dwordx4 v[128:131], v132, s[20:23], 0 offen sc1
	v_cvt_pk_bf16_f32 v120, v120, v121
	v_cvt_pk_bf16_f32 v121, v122, v123
	v_cvt_pk_bf16_f32 v122, v116, v117
	v_cvt_pk_bf16_f32 v123, v118, v119
	buffer_store_dwordx4 v[120:123], v132, s[20:23], s2 offen sc1
	s_movk_i32 s2, 0x800
	v_cvt_pk_bf16_f32 v112, v112, v113
	v_cvt_pk_bf16_f32 v113, v114, v115
	v_cvt_pk_bf16_f32 v114, v108, v109
	v_cvt_pk_bf16_f32 v115, v110, v111
	buffer_store_dwordx4 v[112:115], v132, s[20:23], s2 offen sc1
	s_movk_i32 s2, 0xc00
	v_cvt_pk_bf16_f32 v104, v104, v105
	v_cvt_pk_bf16_f32 v105, v106, v107
	v_cvt_pk_bf16_f32 v106, v100, v101
	v_cvt_pk_bf16_f32 v107, v102, v103
	buffer_store_dwordx4 v[104:107], v132, s[20:23], s2 offen sc1
	s_movk_i32 s2, 0x1000
	v_cvt_pk_bf16_f32 v96, v96, v97
	v_cvt_pk_bf16_f32 v97, v98, v99
	v_cvt_pk_bf16_f32 v98, v92, v93
	v_cvt_pk_bf16_f32 v99, v94, v95
	buffer_store_dwordx4 v[96:99], v132, s[20:23], s2 offen sc1
	s_movk_i32 s2, 0x1400
	v_cvt_pk_bf16_f32 v88, v88, v89
	v_cvt_pk_bf16_f32 v89, v90, v91
	v_cvt_pk_bf16_f32 v90, v84, v85
	v_cvt_pk_bf16_f32 v91, v86, v87
	buffer_store_dwordx4 v[88:91], v132, s[20:23], s2 offen sc1
	s_movk_i32 s2, 0x1800
	v_cvt_pk_bf16_f32 v80, v80, v81
	v_cvt_pk_bf16_f32 v81, v82, v83
	v_cvt_pk_bf16_f32 v82, v76, v77
	v_cvt_pk_bf16_f32 v83, v78, v79
	buffer_store_dwordx4 v[80:83], v132, s[20:23], s2 offen sc1
	s_movk_i32 s2, 0x1c00
	v_cvt_pk_bf16_f32 v72, v72, v73
	v_cvt_pk_bf16_f32 v73, v74, v75
	v_cvt_pk_bf16_f32 v74, v68, v69
	v_cvt_pk_bf16_f32 v75, v70, v71
	buffer_store_dwordx4 v[72:75], v132, s[20:23], s2 offen sc1
	s_movk_i32 s2, 0x2000
	v_cvt_pk_bf16_f32 v64, v64, v65
	v_cvt_pk_bf16_f32 v65, v66, v67
	v_cvt_pk_bf16_f32 v66, v52, v53
	v_cvt_pk_bf16_f32 v67, v54, v55
	buffer_store_dwordx4 v[64:67], v132, s[20:23], s2 offen sc1
	s_movk_i32 s2, 0x2400
	v_cvt_pk_bf16_f32 v32, v32, v33
	v_cvt_pk_bf16_f32 v33, v34, v35
	v_cvt_pk_bf16_f32 v34, v20, v21
	v_cvt_pk_bf16_f32 v35, v22, v23
	buffer_store_dwordx4 v[32:35], v132, s[20:23], s2 offen sc1
	s_movk_i32 s2, 0x2800
	v_cvt_pk_bf16_f32 v16, v16, v17
	v_cvt_pk_bf16_f32 v17, v18, v19
	v_cvt_pk_bf16_f32 v18, v12, v13
	v_cvt_pk_bf16_f32 v19, v14, v15
	buffer_store_dwordx4 v[16:19], v132, s[20:23], s2 offen sc1
	s_movk_i32 s2, 0x2c00
	v_cvt_pk_bf16_f32 v8, v8, v9
	v_cvt_pk_bf16_f32 v9, v10, v11
	v_cvt_pk_bf16_f32 v10, v4, v5
	v_cvt_pk_bf16_f32 v11, v6, v7
	buffer_store_dwordx4 v[8:11], v132, s[20:23], s2 offen sc1
	s_movk_i32 s2, 0x3000
	v_cvt_pk_bf16_f32 v4, v60, v61
	v_cvt_pk_bf16_f32 v5, v62, v63
	v_cvt_pk_bf16_f32 v6, v56, v57
	v_cvt_pk_bf16_f32 v7, v58, v59
	buffer_store_dwordx4 v[4:7], v132, s[20:23], s2 offen sc1
	s_movk_i32 s2, 0x3400
	v_cvt_pk_bf16_f32 v4, v48, v49
	v_cvt_pk_bf16_f32 v5, v50, v51
	v_cvt_pk_bf16_f32 v6, v44, v45
	v_cvt_pk_bf16_f32 v7, v46, v47
	buffer_store_dwordx4 v[4:7], v132, s[20:23], s2 offen sc1
	s_movk_i32 s2, 0x3800
	v_cvt_pk_bf16_f32 v4, v40, v41
	v_cvt_pk_bf16_f32 v5, v42, v43
	v_cvt_pk_bf16_f32 v6, v36, v37
	v_cvt_pk_bf16_f32 v7, v38, v39
	buffer_store_dwordx4 v[4:7], v132, s[20:23], s2 offen sc1
	s_movk_i32 s2, 0x3c00
	v_cvt_pk_bf16_f32 v4, v28, v29
	v_cvt_pk_bf16_f32 v5, v30, v31
	v_cvt_pk_bf16_f32 v6, v24, v25
	v_cvt_pk_bf16_f32 v7, v26, v27
	buffer_store_dwordx4 v[4:7], v132, s[20:23], s2 offen sc1
	s_and_b64 vcc, exec, s[36:37]
	s_mov_b64 s[12:13], -1
	s_cbranch_vccnz .LBB0_156
	s_branch .LBB0_457

; __device__ __forceinline__ unsigned cvt_pk_bf16(float lo, float hi) { unsigned r; asm volatile("v_cvt_pk_bf16_f32 %0, %1, %2" : "=v"(r) : "v"(lo), "v"(hi)); return r; }
; template <class Desc, class Epi, bool ALIGN_EPI>
; __device__ __forceinline__ void gemm_phase(LAS unsigned char* lds, const Desc& D, const Epi& E, int G, int c) {
;     ...
;           if constexpr (Desc::SPLIT) {
;               if (cur.sp >= 0) {
;                   const __amdgpu_buffer_rsrc_t rs = __builtin_amdgcn_make_buffer_rsrc((void*)(D.slab + (size_t)(cur.uid * Desc::S + cur.sp) * SLAB_B), (short)0, SLAB_B, 0x00020000);
;                   const int loff = ((wr_ * 4 + wc_) * 16 * 64 + ln_) * 16;
; #pragma unroll
;                   for (int rp = 0; rp < 16; ++rp) { const f32x4 a0 = acc[rp >> 3][(rp >> 2) & 1][rp & 3][0], a1 = acc[rp >> 3][(rp >> 2) & 1][rp & 3][1];
;                       u32x4 w; w.x = cvt_pk_bf16(a0[0], a0[1]); w.y = cvt_pk_bf16(a0[2], a0[3]); w.z = cvt_pk_bf16(a1[0], a1[1]); w.w = cvt_pk_bf16(a1[2], a1[3]);
;                       __builtin_amdgcn_raw_buffer_store_b128(w, rs, loff, rp * 1024, 0); }
;                   slabbed = true;
;               }
.LBB0_1186:
	s_and_b64 vcc, exec, s[12:13]
	s_cbranch_vccz .LBB0_1185
	s_lshl_b32 s0, s60, 3
	s_add_i32 s0, s0, s23
	s_ashr_i32 s1, s0, 31
	s_lshl_b64 s[0:1], s[0:1], 17
	s_add_u32 s20, s81, s0
	s_addc_u32 s0, s83, s1
	s_and_b32 s21, s0, 0xffff
	s_lshl_b32 s0, s3, 16
	s_lshl_b32 s1, s2, 14
	s_add_i32 s0, s0, s1
	s_mov_b32 s23, s22
	v_lshl_add_u32 v132, v239, 4, s0
	s_movk_i32 s0, 0x400
	v_cvt_pk_bf16_f32 v128, v128, v129
	v_cvt_pk_bf16_f32 v129, v130, v131
	v_cvt_pk_bf16_f32 v130, v124, v125
	v_cvt_pk_bf16_f32 v131, v126, v127
	buffer_store_dwordx4 v[128:131], v132, s[20:23], 0 offen sc1
	v_cvt_pk_bf16_f32 v120, v120, v121
	v_cvt_pk_bf16_f32 v121, v122, v123
	v_cvt_pk_bf16_f32 v122, v116, v117
	v_cvt_pk_bf16_f32 v123, v118, v119
	buffer_store_dwordx4 v[120:123], v132, s[20:23], s0 offen sc1
	s_movk_i32 s0, 0x800
	v_cvt_pk_bf16_f32 v112, v112, v113
	v_cvt_pk_bf16_f32 v113, v114, v115
	v_cvt_pk_bf16_f32 v114, v108, v109
	v_cvt_pk_bf16_f32 v115, v110, v111
	buffer_store_dwordx4 v[112:115], v132, s[20:23], s0 offen sc1
	s_movk_i32 s0, 0xc00
	v_cvt_pk_bf16_f32 v104, v104, v105
	v_cvt_pk_bf16_f32 v105, v106, v107
	v_cvt_pk_bf16_f32 v106, v100, v101
	v_cvt_pk_bf16_f32 v107, v102, v103
	buffer_store_dwordx4 v[104:107], v132, s[20:23], s0 offen sc1
	s_movk_i32 s0, 0x1000
	v_cvt_pk_bf16_f32 v96, v96, v97
	v_cvt_pk_bf16_f32 v97, v98, v99
	v_cvt_pk_bf16_f32 v98, v92, v93
	v_cvt_pk_bf16_f32 v99, v94, v95
	buffer_store_dwordx4 v[96:99], v132, s[20:23], s0 offen sc1
	s_movk_i32 s0, 0x1400
	v_cvt_pk_bf16_f32 v88, v88, v89
	v_cvt_pk_bf16_f32 v89, v90, v91
	v_cvt_pk_bf16_f32 v90, v80, v81
	v_cvt_pk_bf16_f32 v91, v82, v83
	buffer_store_dwordx4 v[88:91], v132, s[20:23], s0 offen sc1
	s_movk_i32 s0, 0x1800
	v_cvt_pk_bf16_f32 v64, v64, v65
	v_cvt_pk_bf16_f32 v65, v66, v67
	v_cvt_pk_bf16_f32 v66, v52, v53
	v_cvt_pk_bf16_f32 v67, v54, v55
	buffer_store_dwordx4 v[64:67], v132, s[20:23], s0 offen sc1
	s_movk_i32 s0, 0x1c00
	v_cvt_pk_bf16_f32 v32, v32, v33
	v_cvt_pk_bf16_f32 v33, v34, v35
	v_cvt_pk_bf16_f32 v34, v20, v21
	v_cvt_pk_bf16_f32 v35, v22, v23
	buffer_store_dwordx4 v[32:35], v132, s[20:23], s0 offen sc1
	s_movk_i32 s0, 0x2000
	v_cvt_pk_bf16_f32 v20, v84, v85
	v_cvt_pk_bf16_f32 v21, v86, v87
	v_cvt_pk_bf16_f32 v22, v76, v77
	v_cvt_pk_bf16_f32 v23, v78, v79
	buffer_store_dwordx4 v[20:23], v132, s[20:23], s0 offen sc1
	s_movk_i32 s0, 0x2400
	v_cvt_pk_bf16_f32 v20, v72, v73
	v_cvt_pk_bf16_f32 v21, v74, v75
	v_cvt_pk_bf16_f32 v22, v68, v69
	v_cvt_pk_bf16_f32 v23, v70, v71
	buffer_store_dwordx4 v[20:23], v132, s[20:23], s0 offen sc1
	s_movk_i32 s0, 0x2800
	v_cvt_pk_bf16_f32 v20, v60, v61
	v_cvt_pk_bf16_f32 v21, v62, v63
	v_cvt_pk_bf16_f32 v22, v56, v57
	v_cvt_pk_bf16_f32 v23, v58, v59
	buffer_store_dwordx4 v[20:23], v132, s[20:23], s0 offen sc1
	s_movk_i32 s0, 0x2c00
	v_cvt_pk_bf16_f32 v20, v48, v49
	v_cvt_pk_bf16_f32 v21, v50, v51
	v_cvt_pk_bf16_f32 v22, v44, v45
	v_cvt_pk_bf16_f32 v23, v46, v47
	buffer_store_dwordx4 v[20:23], v132, s[20:23], s0 offen sc1
	s_movk_i32 s0, 0x3000
	v_cvt_pk_bf16_f32 v20, v40, v41
	v_cvt_pk_bf16_f32 v21, v42, v43
	v_cvt_pk_bf16_f32 v22, v36, v37
	v_cvt_pk_bf16_f32 v23, v38, v39
	buffer_store_dwordx4 v[20:23], v132, s[20:23], s0 offen sc1
	s_movk_i32 s0, 0x3400
	v_cvt_pk_bf16_f32 v20, v28, v29
	v_cvt_pk_bf16_f32 v21, v30, v31
	v_cvt_pk_bf16_f32 v22, v24, v25
	v_cvt_pk_bf16_f32 v23, v26, v27
	buffer_store_dwordx4 v[20:23], v132, s[20:23], s0 offen sc1
	s_movk_i32 s0, 0x3800
	v_cvt_pk_bf16_f32 v16, v16, v17
	v_cvt_pk_bf16_f32 v17, v18, v19
	v_cvt_pk_bf16_f32 v18, v12, v13
	v_cvt_pk_bf16_f32 v19, v14, v15
	buffer_store_dwordx4 v[16:19], v132, s[20:23], s0 offen sc1
	s_movk_i32 s0, 0x3c00
	v_cvt_pk_bf16_f32 v8, v8, v9
	v_cvt_pk_bf16_f32 v9, v10, v11
	v_cvt_pk_bf16_f32 v10, v4, v5
	v_cvt_pk_bf16_f32 v11, v6, v7
	buffer_store_dwordx4 v[8:11], v132, s[20:23], s0 offen sc1
	s_and_b64 vcc, exec, s[36:37]
	s_mov_b64 s[0:1], -1
	s_cbranch_vccnz .LBB0_1150

; __device__ __forceinline__ unsigned cvt_pk_bf16(float lo, float hi) { unsigned r; asm volatile("v_cvt_pk_bf16_f32 %0, %1, %2" : "=v"(r) : "v"(lo), "v"(hi)); return r; }
; template <class Desc, class Epi, bool ALIGN_EPI>
; __device__ __forceinline__ void gemm_phase(LAS unsigned char* lds, const Desc& D, const Epi& E, int G, int c) {
;     ...
;           if constexpr (Desc::SPLIT) {
;               if (cur.sp >= 0) {
;                   const __amdgpu_buffer_rsrc_t rs = __builtin_amdgcn_make_buffer_rsrc((void*)(D.slab + (size_t)(cur.uid * Desc::S + cur.sp) * SLAB_B), (short)0, SLAB_B, 0x00020000);
;                   const int loff = ((wr_ * 4 + wc_) * 16 * 64 + ln_) * 16;
; #pragma unroll
;                   for (int rp = 0; rp < 16; ++rp) { const f32x4 a0 = acc[rp >> 3][(rp >> 2) & 1][rp & 3][0], a1 = acc[rp >> 3][(rp >> 2) & 1][rp & 3][1];
;                       u32x4 w; w.x = cvt_pk_bf16(a0[0], a0[1]); w.y = cvt_pk_bf16(a0[2], a0[3]); w.z = cvt_pk_bf16(a1[0], a1[1]); w.w = cvt_pk_bf16(a1[2], a1[3]);
;                       __builtin_amdgcn_raw_buffer_store_b128(w, rs, loff, rp * 1024, 0); }
;                   slabbed = true;
;               }
.LBB0_1597:
	s_lshl_b32 s2, s66, 1
	s_add_i32 s2, s2, s23
	s_ashr_i32 s3, s2, 31
	s_lshl_b64 s[2:3], s[2:3], 17
	s_add_u32 s20, s81, s2
	s_addc_u32 s2, s83, s3
	s_and_b32 s21, s2, 0xffff
	s_lshl_b32 s2, s30, 16
	s_lshl_b32 s3, s14, 14
	s_add_i32 s2, s2, s3
	s_mov_b32 s23, s22
	v_lshl_add_u32 v140, v166, 4, s2
	s_movk_i32 s2, 0x400
	v_cvt_pk_bf16_f32 v128, v128, v129
	v_cvt_pk_bf16_f32 v129, v130, v131
	v_cvt_pk_bf16_f32 v130, v124, v125
	v_cvt_pk_bf16_f32 v131, v126, v127
	buffer_store_dwordx4 v[128:131], v140, s[20:23], 0 offen sc1
	v_cvt_pk_bf16_f32 v120, v120, v121
	v_cvt_pk_bf16_f32 v121, v122, v123
	v_cvt_pk_bf16_f32 v122, v116, v117
	v_cvt_pk_bf16_f32 v123, v118, v119
	buffer_store_dwordx4 v[120:123], v140, s[20:23], s2 offen sc1
	s_movk_i32 s2, 0x800
	v_cvt_pk_bf16_f32 v112, v112, v113
	v_cvt_pk_bf16_f32 v113, v114, v115
	v_cvt_pk_bf16_f32 v114, v108, v109
	v_cvt_pk_bf16_f32 v115, v110, v111
	buffer_store_dwordx4 v[112:115], v140, s[20:23], s2 offen sc1
	s_movk_i32 s2, 0xc00
	v_cvt_pk_bf16_f32 v104, v104, v105
	v_cvt_pk_bf16_f32 v105, v106, v107
	v_cvt_pk_bf16_f32 v106, v100, v101
	v_cvt_pk_bf16_f32 v107, v102, v103
	buffer_store_dwordx4 v[104:107], v140, s[20:23], s2 offen sc1
	s_movk_i32 s2, 0x1000
	v_cvt_pk_bf16_f32 v96, v96, v97
	v_cvt_pk_bf16_f32 v97, v98, v99
	v_cvt_pk_bf16_f32 v98, v92, v93
	v_cvt_pk_bf16_f32 v99, v94, v95
	buffer_store_dwordx4 v[96:99], v140, s[20:23], s2 offen sc1
	s_movk_i32 s2, 0x1400
	v_cvt_pk_bf16_f32 v88, v88, v89
	v_cvt_pk_bf16_f32 v89, v90, v91
	v_cvt_pk_bf16_f32 v90, v84, v85
	v_cvt_pk_bf16_f32 v91, v86, v87
	buffer_store_dwordx4 v[88:91], v140, s[20:23], s2 offen sc1
	s_movk_i32 s2, 0x1800
	v_cvt_pk_bf16_f32 v80, v80, v81
	v_cvt_pk_bf16_f32 v81, v82, v83
	v_cvt_pk_bf16_f32 v82, v76, v77
	v_cvt_pk_bf16_f32 v83, v78, v79
	buffer_store_dwordx4 v[80:83], v140, s[20:23], s2 offen sc1
	s_movk_i32 s2, 0x1c00
	v_cvt_pk_bf16_f32 v72, v72, v73
	v_cvt_pk_bf16_f32 v73, v74, v75
	v_cvt_pk_bf16_f32 v74, v68, v69
	v_cvt_pk_bf16_f32 v75, v70, v71
	buffer_store_dwordx4 v[72:75], v140, s[20:23], s2 offen sc1
	s_movk_i32 s2, 0x2000
	v_cvt_pk_bf16_f32 v64, v64, v65
	v_cvt_pk_bf16_f32 v65, v66, v67
	v_cvt_pk_bf16_f32 v66, v52, v53
	v_cvt_pk_bf16_f32 v67, v54, v55
	buffer_store_dwordx4 v[64:67], v140, s[20:23], s2 offen sc1
	s_movk_i32 s2, 0x2400
	v_cvt_pk_bf16_f32 v32, v32, v33
	v_cvt_pk_bf16_f32 v33, v34, v35
	v_cvt_pk_bf16_f32 v34, v20, v21
	v_cvt_pk_bf16_f32 v35, v22, v23
	buffer_store_dwordx4 v[32:35], v140, s[20:23], s2 offen sc1
	s_movk_i32 s2, 0x2800
	v_cvt_pk_bf16_f32 v16, v16, v17
	v_cvt_pk_bf16_f32 v17, v18, v19
	v_cvt_pk_bf16_f32 v18, v12, v13
	v_cvt_pk_bf16_f32 v19, v14, v15
	buffer_store_dwordx4 v[16:19], v140, s[20:23], s2 offen sc1
	s_movk_i32 s2, 0x2c00
	v_cvt_pk_bf16_f32 v8, v8, v9
	v_cvt_pk_bf16_f32 v9, v10, v11
	v_cvt_pk_bf16_f32 v10, v4, v5
	v_cvt_pk_bf16_f32 v11, v6, v7
	buffer_store_dwordx4 v[8:11], v140, s[20:23], s2 offen sc1
	s_movk_i32 s2, 0x3000
	v_cvt_pk_bf16_f32 v4, v60, v61
	v_cvt_pk_bf16_f32 v5, v62, v63
	v_cvt_pk_bf16_f32 v6, v56, v57
	v_cvt_pk_bf16_f32 v7, v58, v59
	buffer_store_dwordx4 v[4:7], v140, s[20:23], s2 offen sc1
	s_movk_i32 s2, 0x3400
	v_cvt_pk_bf16_f32 v4, v48, v49
	v_cvt_pk_bf16_f32 v5, v50, v51
	v_cvt_pk_bf16_f32 v6, v44, v45
	v_cvt_pk_bf16_f32 v7, v46, v47
	buffer_store_dwordx4 v[4:7], v140, s[20:23], s2 offen sc1
	s_movk_i32 s2, 0x3800
	v_cvt_pk_bf16_f32 v4, v40, v41
	v_cvt_pk_bf16_f32 v5, v42, v43
	v_cvt_pk_bf16_f32 v6, v36, v37
	v_cvt_pk_bf16_f32 v7, v38, v39
	buffer_store_dwordx4 v[4:7], v140, s[20:23], s2 offen sc1
	s_movk_i32 s2, 0x3c00
	v_cvt_pk_bf16_f32 v4, v28, v29
	v_cvt_pk_bf16_f32 v5, v30, v31
	v_cvt_pk_bf16_f32 v6, v24, v25
	v_cvt_pk_bf16_f32 v7, v26, v27
	buffer_store_dwordx4 v[4:7], v140, s[20:23], s2 offen sc1
	s_andn2_b64 vcc, exec, s[40:41]
	s_mov_b64 s[12:13], -1
	s_cbranch_vccnz .LBB0_1570

; __device__ __forceinline__ unsigned cvt_pk_bf16(float lo, float hi) { unsigned r; asm volatile("v_cvt_pk_bf16_f32 %0, %1, %2" : "=v"(r) : "v"(lo), "v"(hi)); return r; }
; template <class Desc, class Epi, bool ALIGN_EPI>
; __device__ __forceinline__ void gemm_phase(LAS unsigned char* lds, const Desc& D, const Epi& E, int G, int c) {
;     ...
;           if constexpr (Desc::SPLIT) {
;               if (cur.sp >= 0) {
;                   const __amdgpu_buffer_rsrc_t rs = __builtin_amdgcn_make_buffer_rsrc((void*)(D.slab + (size_t)(cur.uid * Desc::S + cur.sp) * SLAB_B), (short)0, SLAB_B, 0x00020000);
;                   const int loff = ((wr_ * 4 + wc_) * 16 * 64 + ln_) * 16;
; #pragma unroll
;                   for (int rp = 0; rp < 16; ++rp) { const f32x4 a0 = acc[rp >> 3][(rp >> 2) & 1][rp & 3][0], a1 = acc[rp >> 3][(rp >> 2) & 1][rp & 3][1];
;                       u32x4 w; w.x = cvt_pk_bf16(a0[0], a0[1]); w.y = cvt_pk_bf16(a0[2], a0[3]); w.z = cvt_pk_bf16(a1[0], a1[1]); w.w = cvt_pk_bf16(a1[2], a1[3]);
;                       __builtin_amdgcn_raw_buffer_store_b128(w, rs, loff, rp * 1024, 0); }
;                   slabbed = true;
;               }
.LBB0_1797:
	s_and_b64 vcc, exec, s[12:13]
	s_cbranch_vccz .LBB0_1866
	s_lshl_b32 s2, s68, 3
	s_add_i32 s2, s2, s23
	s_ashr_i32 s3, s2, 31
	s_lshl_b64 s[2:3], s[2:3], 17
	s_add_u32 s20, s81, s2
	s_addc_u32 s2, s83, s3
	s_and_b32 s21, s2, 0xffff
	s_lshl_b32 s2, s14, 16
	s_lshl_b32 s3, s18, 14
	s_add_i32 s2, s2, s3
	s_mov_b32 s23, s22
	v_lshl_add_u32 v132, v249, 4, s2
	s_movk_i32 s2, 0x400
	v_cvt_pk_bf16_f32 v128, v128, v129
	v_cvt_pk_bf16_f32 v129, v130, v131
	v_cvt_pk_bf16_f32 v130, v124, v125
	v_cvt_pk_bf16_f32 v131, v126, v127
	buffer_store_dwordx4 v[128:131], v132, s[20:23], 0 offen sc1
	v_cvt_pk_bf16_f32 v120, v120, v121
	v_cvt_pk_bf16_f32 v121, v122, v123
	v_cvt_pk_bf16_f32 v122, v116, v117
	v_cvt_pk_bf16_f32 v123, v118, v119
	buffer_store_dwordx4 v[120:123], v132, s[20:23], s2 offen sc1
	s_movk_i32 s2, 0x800
	v_cvt_pk_bf16_f32 v112, v112, v113
	v_cvt_pk_bf16_f32 v113, v114, v115
	v_cvt_pk_bf16_f32 v114, v108, v109
	v_cvt_pk_bf16_f32 v115, v110, v111
	buffer_store_dwordx4 v[112:115], v132, s[20:23], s2 offen sc1
	s_movk_i32 s2, 0xc00
	v_cvt_pk_bf16_f32 v104, v104, v105
	v_cvt_pk_bf16_f32 v105, v106, v107
	v_cvt_pk_bf16_f32 v106, v100, v101
	v_cvt_pk_bf16_f32 v107, v102, v103
	buffer_store_dwordx4 v[104:107], v132, s[20:23], s2 offen sc1
	s_movk_i32 s2, 0x1000
	v_cvt_pk_bf16_f32 v96, v96, v97
	v_cvt_pk_bf16_f32 v97, v98, v99
	v_cvt_pk_bf16_f32 v98, v92, v93
	v_cvt_pk_bf16_f32 v99, v94, v95
	buffer_store_dwordx4 v[96:99], v132, s[20:23], s2 offen sc1
	s_movk_i32 s2, 0x1400
	v_cvt_pk_bf16_f32 v88, v88, v89
	v_cvt_pk_bf16_f32 v89, v90, v91
	v_cvt_pk_bf16_f32 v90, v80, v81
	v_cvt_pk_bf16_f32 v91, v82, v83
	buffer_store_dwordx4 v[88:91], v132, s[20:23], s2 offen sc1
	s_movk_i32 s2, 0x1800
	v_cvt_pk_bf16_f32 v64, v64, v65
	v_cvt_pk_bf16_f32 v65, v66, v67
	v_cvt_pk_bf16_f32 v66, v52, v53
	v_cvt_pk_bf16_f32 v67, v54, v55
	buffer_store_dwordx4 v[64:67], v132, s[20:23], s2 offen sc1
	s_movk_i32 s2, 0x1c00
	v_cvt_pk_bf16_f32 v32, v32, v33
	v_cvt_pk_bf16_f32 v33, v34, v35
	v_cvt_pk_bf16_f32 v34, v20, v21
	v_cvt_pk_bf16_f32 v35, v22, v23
	buffer_store_dwordx4 v[32:35], v132, s[20:23], s2 offen sc1
	s_movk_i32 s2, 0x2000
	v_cvt_pk_bf16_f32 v20, v84, v85
	v_cvt_pk_bf16_f32 v21, v86, v87
	v_cvt_pk_bf16_f32 v22, v76, v77
	v_cvt_pk_bf16_f32 v23, v78, v79
	buffer_store_dwordx4 v[20:23], v132, s[20:23], s2 offen sc1
	s_movk_i32 s2, 0x2400
	v_cvt_pk_bf16_f32 v20, v72, v73
	v_cvt_pk_bf16_f32 v21, v74, v75
	v_cvt_pk_bf16_f32 v22, v68, v69
	v_cvt_pk_bf16_f32 v23, v70, v71
	buffer_store_dwordx4 v[20:23], v132, s[20:23], s2 offen sc1
	s_movk_i32 s2, 0x2800
	v_cvt_pk_bf16_f32 v20, v60, v61
	v_cvt_pk_bf16_f32 v21, v62, v63
	v_cvt_pk_bf16_f32 v22, v56, v57
	v_cvt_pk_bf16_f32 v23, v58, v59
	buffer_store_dwordx4 v[20:23], v132, s[20:23], s2 offen sc1
	s_movk_i32 s2, 0x2c00
	v_cvt_pk_bf16_f32 v20, v48, v49
	v_cvt_pk_bf16_f32 v21, v50, v51
	v_cvt_pk_bf16_f32 v22, v44, v45
	v_cvt_pk_bf16_f32 v23, v46, v47
	buffer_store_dwordx4 v[20:23], v132, s[20:23], s2 offen sc1
	s_movk_i32 s2, 0x3000
	v_cvt_pk_bf16_f32 v20, v40, v41
	v_cvt_pk_bf16_f32 v21, v42, v43
	v_cvt_pk_bf16_f32 v22, v36, v37
	v_cvt_pk_bf16_f32 v23, v38, v39
	buffer_store_dwordx4 v[20:23], v132, s[20:23], s2 offen sc1
	s_movk_i32 s2, 0x3400
	v_cvt_pk_bf16_f32 v20, v28, v29
	v_cvt_pk_bf16_f32 v21, v30, v31
	v_cvt_pk_bf16_f32 v22, v24, v25
	v_cvt_pk_bf16_f32 v23, v26, v27
	buffer_store_dwordx4 v[20:23], v132, s[20:23], s2 offen sc1
	s_movk_i32 s2, 0x3800
	v_cvt_pk_bf16_f32 v16, v16, v17
	v_cvt_pk_bf16_f32 v17, v18, v19
	v_cvt_pk_bf16_f32 v18, v12, v13
	v_cvt_pk_bf16_f32 v19, v14, v15
	buffer_store_dwordx4 v[16:19], v132, s[20:23], s2 offen sc1
	s_movk_i32 s2, 0x3c00
	v_cvt_pk_bf16_f32 v8, v8, v9
	v_cvt_pk_bf16_f32 v9, v10, v11
	v_cvt_pk_bf16_f32 v10, v4, v5
	v_cvt_pk_bf16_f32 v11, v6, v7
	buffer_store_dwordx4 v[8:11], v132, s[20:23], s2 offen sc1
	s_and_b64 vcc, exec, s[36:37]
	s_mov_b64 s[12:13], -1
	s_cbranch_vccnz .LBB0_1749
	s_branch .LBB0_1867
